# C1 + EpiWin (phase 1): per-row scale loads hoisted to the unit start, epilogue no longer drains the next unit's LDS-DMA prefetch
# baseline (speedup 1.0000x reference)
;     __device__ bool next(int i, Unit& u) const {
;         const long L = (long)base + (long)i * G + c; if (L >= cap) return false;
;         int wgid = (int)L; { const int q = nwg / NXCD, r = nwg % NXCD, xcd = wgid % NXCD, off = wgid / NXCD; wgid = (xcd < r ? xcd * (q + 1) : r * (q + 1) + (xcd - r) * q) + off; }
;         const int nig = WGM * nN, gid = wgid / nig, fm = gid * WGM, gsz = (nM - fm) < WGM ? (nM - fm) : WGM;
;         u.pm = fm + ((wgid % nig) % gsz); u.pn = (wgid % nig) / gsz; return true;
;     }
;     __device__ __forceinline__ void operator()(const f32x4 (&acc)[2][2][4][2], const Unit& u, int wr, int wc, int fr, int fq) const {
;         const int row0 = u.pm * 256 + wr * 64 + fr;
;         const bool hg = u.pn < 8; bf16_t* base = hg ? phg : prw; const int ld = hg ? HGC : RWC; const int col0 = (hg ? u.pn : u.pn - 8) * 256 + wc * 32 + 8 * fq;
;         float sv[8];
; #pragma unroll
;         for (int i = 0; i < 8; ++i) sv[i] = rs0[row0 + (i >> 2) * 128 + (i & 3) * 16];
.LBB0_181:
	s_lshl_b32 s1, s8, 8
	s_add_i32 s1, s1, s83
	v_or_b32_e32 v254, s1, v145
	v_ashrrev_i32_e32 v255, 31, v254
	v_lshl_add_u64 v[254:255], v[254:255], 2, s[12:13]
	global_load_dword v238, v[254:255], off
	global_load_dword v240, v[254:255], off offset:64
	global_load_dword v242, v[254:255], off offset:128
	global_load_dword v244, v[254:255], off offset:192
	global_load_dword v246, v[254:255], off offset:512
	global_load_dword v248, v[254:255], off offset:576
	global_load_dword v250, v[254:255], off offset:640
	global_load_dword v252, v[254:255], off offset:704
	s_add_i32 s33, s33, 1
	s_mul_i32 s1, s33, s3
	s_mul_hi_u32 s4, s33, s34
	s_add_i32 s4, s4, s1
	s_mul_i32 s1, s33, s34
	s_add_u32 s64, s1, s2
	s_addc_u32 s65, s4, s82
	v_cmp_gt_i64_e32 vcc, s[64:65], v[142:143]
	v_cmp_lt_i64_e64 s[4:5], s[64:65], v[140:141]
	s_cbranch_vccnz .LBB0_187
	s_ashr_i32 s1, s64, 31
	s_lshr_b32 s1, s1, 29
	s_add_i32 s1, s64, s1
	s_and_b32 s52, s1, -8
	s_sub_i32 s52, s64, s52
	s_cmp_gt_i32 s52, 5
	s_mov_b64 s[54:55], -1
	s_cbranch_scc0 .LBB0_184
	s_mul_i32 s53, s52, 0xf3
	s_add_i32 s53, s53, 6
	s_mov_b64 s[54:55], 0

;     __device__ __forceinline__ void operator()(const f32x4 (&acc)[2][2][4][2], const Unit& u, int wr, int wc, int fr, int fq) const {
;         const int row0 = u.pm * 256 + wr * 64 + fr;
;         const bool hg = u.pn < 8; bf16_t* base = hg ? phg : prw; const int ld = hg ? HGC : RWC; const int col0 = (hg ? u.pn : u.pn - 8) * 256 + wc * 32 + 8 * fq;
;         float sv[8];
; #pragma unroll
;         for (int i = 0; i < 8; ++i) sv[i] = rs0[row0 + (i >> 2) * 128 + (i & 3) * 16];
; #pragma unroll
;         for (int ai = 0; ai < 2; ++ai)
; #pragma unroll
;             for (int m = 0; m < 4; ++m) {
;                 const int row = row0 + ai * 128 + m * 16; const float s = sv[ai * 4 + m]; bf16_t* rowp = base + (size_t)row * ld + col0;
; #pragma unroll
;                 for (int bj = 0; bj < 2; ++bj) *(u32x4*)(rowp + bj * 128) = pack_acc8(acc[ai][bj][m][0], acc[ai][bj][m][1], s);
;                 if (!hg) {
;                     bool last; float* dst;
;                     if (row < NTOKP) { last = (row & 4095) == 4095; dst = psh + (row >> 12) * RWC; } else { const int rr = row - NTOKP; last = (rr & 31) == 31; dst = ssh + (rr >> 5) * RWC; }
;                     if (last) {
; #pragma unroll
;                         for (int bj = 0; bj < 2; ++bj) { *(f32x4*)(dst + col0 + bj * 128) = acc[ai][bj][m][0] * s; *(f32x4*)(dst + col0 + bj * 128 + 4) = acc[ai][bj][m][1] * s; }
;                     }
;                 }
;             }
;     }
.LBB0_191:
	s_lshl_b32 s52, s8, 8
	s_add_i32 s52, s52, s83
	v_or_b32_e32 v148, s52, v145
	v_ashrrev_i32_e32 v149, 31, v148
	v_lshl_add_u64 v[146:147], v[148:149], 2, s[12:13]
	s_lshl_b32 s8, s0, 8
	s_add_i32 s55, s8, 0xfffff800
	s_cmp_gt_i32 s0, 7
	s_cselect_b64 s[70:71], -1, 0
	s_and_b64 s[0:1], s[70:71], exec
	s_mov_b32 s0, 0xa4c0000
	s_cselect_b32 s0, s0, 0x22c0000
	s_movk_i32 s1, 0x700
	s_cselect_b32 s8, s55, s8
	s_cselect_b32 s53, s1, 0x800
	s_add_u32 s0, s92, s0
	v_or_b32_e32 v146, s8, v155
	s_addc_u32 s1, s93, 0
	v_ashrrev_i32_e32 v147, 31, v146
	v_lshl_add_u64 v[150:151], v[146:147], 1, s[0:1]
	v_mad_i64_i32 v[166:167], s[0:1], s53, v148, 0
	v_lshl_add_u64 v[166:167], v[166:167], 1, v[150:151]
	v_pk_mul_f32 v[124:125], v[124:125], v[238:239] op_sel_hi:[1,0]
	v_pk_mul_f32 v[126:127], v[126:127], v[238:239] op_sel_hi:[1,0]
	v_pk_mul_f32 v[120:121], v[120:121], v[238:239] op_sel_hi:[1,0]
	v_cvt_pk_bf16_f32 v124, v124, v125
	v_cvt_pk_bf16_f32 v125, v126, v127
	v_cvt_pk_bf16_f32 v126, v120, v121
	v_pk_mul_f32 v[120:121], v[122:123], v[238:239] op_sel_hi:[1,0]
	v_pk_mul_f32 v[116:117], v[116:117], v[238:239] op_sel_hi:[1,0]
	v_pk_mul_f32 v[118:119], v[118:119], v[238:239] op_sel_hi:[1,0]
	v_pk_mul_f32 v[112:113], v[112:113], v[238:239] op_sel_hi:[1,0]
	v_cvt_pk_bf16_f32 v127, v120, v121
	v_cvt_pk_bf16_f32 v116, v116, v117
	v_cvt_pk_bf16_f32 v117, v118, v119
	v_cvt_pk_bf16_f32 v118, v112, v113
	v_pk_mul_f32 v[112:113], v[114:115], v[238:239] op_sel_hi:[1,0]
	v_or_b32_e32 v120, 16, v148
	v_cvt_pk_bf16_f32 v119, v112, v113
	v_mad_i64_i32 v[112:113], s[0:1], s53, v120, 0
	global_store_dwordx4 v[166:167], v[116:119], off offset:256
	v_pk_mul_f32 v[114:115], v[110:111], v[240:241] op_sel_hi:[1,0]
	global_store_dwordx4 v[166:167], v[124:127], off
	v_lshl_add_u64 v[116:117], v[112:113], 1, v[150:151]
	v_pk_mul_f32 v[112:113], v[108:109], v[240:241] op_sel_hi:[1,0]
	v_pk_mul_f32 v[118:119], v[106:107], v[240:241] op_sel_hi:[1,0]
	v_cvt_pk_bf16_f32 v112, v112, v113
	v_cvt_pk_bf16_f32 v113, v114, v115
	v_pk_mul_f32 v[114:115], v[104:105], v[240:241] op_sel_hi:[1,0]
	v_cmp_lt_i32_e32 vcc, s96, v120
	v_cvt_pk_bf16_f32 v114, v114, v115
	v_cvt_pk_bf16_f32 v115, v118, v119
	global_store_dwordx4 v[116:117], v[112:115], off
	v_pk_mul_f32 v[118:119], v[90:91], v[240:241] op_sel_hi:[1,0]
	s_and_b64 s[0:1], s[70:71], vcc
	v_pk_mul_f32 v[112:113], v[100:101], v[240:241] op_sel_hi:[1,0]
	v_pk_mul_f32 v[114:115], v[102:103], v[240:241] op_sel_hi:[1,0]
	v_cvt_pk_bf16_f32 v112, v112, v113
	v_cvt_pk_bf16_f32 v113, v114, v115
	v_pk_mul_f32 v[114:115], v[88:89], v[240:241] op_sel_hi:[1,0]
	s_and_b64 s[58:59], s[38:39], s[0:1]
	v_cvt_pk_bf16_f32 v114, v114, v115
	v_cvt_pk_bf16_f32 v115, v118, v119
	global_store_dwordx4 v[116:117], v[112:115], off offset:256
	s_and_saveexec_b64 s[0:1], s[58:59]
	s_cbranch_execz .LBB0_193
	s_add_i32 s8, s52, 0xffff8010
	s_lshr_b32 s8, s8, 5
	s_mulk_i32 s8, 0x700
	s_lshl_b64 s[58:59], s[8:9], 2
	s_add_u32 s58, s80, s58
	s_addc_u32 s59, s81, s59
	v_lshl_add_u64 v[112:113], v[146:147], 2, s[58:59]
	v_pk_mul_f32 v[110:111], v[110:111], v[240:241] op_sel_hi:[1,0]
	v_pk_mul_f32 v[108:109], v[108:109], v[240:241] op_sel_hi:[1,0]
	v_pk_mul_f32 v[106:107], v[106:107], v[240:241] op_sel_hi:[1,0]
	v_pk_mul_f32 v[104:105], v[104:105], v[240:241] op_sel_hi:[1,0]
	v_pk_mul_f32 v[102:103], v[102:103], v[240:241] op_sel_hi:[1,0]
	v_pk_mul_f32 v[100:101], v[100:101], v[240:241] op_sel_hi:[1,0]
	v_pk_mul_f32 v[90:91], v[90:91], v[240:241] op_sel_hi:[1,0]
	v_pk_mul_f32 v[88:89], v[88:89], v[240:241] op_sel_hi:[1,0]
	global_store_dwordx4 v[112:113], v[108:111], off
	global_store_dwordx4 v[112:113], v[104:107], off offset:16
	global_store_dwordx4 v[112:113], v[100:103], off offset:512
	global_store_dwordx4 v[112:113], v[88:91], off offset:528
;     __device__ __forceinline__ void operator()(const f32x4 (&acc)[2][2][4][2], const Unit& u, int wr, int wc, int fr, int fq) const {
;     ...
;             for (int m = 0; m < 4; ++m) {
;                 const int row = row0 + ai * 128 + m * 16; const float s = sv[ai * 4 + m]; bf16_t* rowp = base + (size_t)row * ld + col0;
; #pragma unroll
;                 for (int bj = 0; bj < 2; ++bj) *(u32x4*)(rowp + bj * 128) = pack_acc8(acc[ai][bj][m][0], acc[ai][bj][m][1], s);
;                 if (!hg) {
;                     bool last; float* dst;
;                     if (row < NTOKP) { last = (row & 4095) == 4095; dst = psh + (row >> 12) * RWC; } else { const int rr = row - NTOKP; last = (rr & 31) == 31; dst = ssh + (rr >> 5) * RWC; }
;                     if (last) {
; #pragma unroll
;                         for (int bj = 0; bj < 2; ++bj) { *(f32x4*)(dst + col0 + bj * 128) = acc[ai][bj][m][0] * s; *(f32x4*)(dst + col0 + bj * 128 + 4) = acc[ai][bj][m][1] * s; }
;                     }
;                 }
;             }
.LBB0_193:
	s_or_b64 exec, exec, s[0:1]
	s_nop 0
	v_or_b32_e32 v88, 32, v148
	v_mad_i64_i32 v[88:89], s[0:1], s53, v88, 0
	v_pk_mul_f32 v[84:85], v[84:85], v[242:243] op_sel_hi:[1,0]
	v_pk_mul_f32 v[86:87], v[86:87], v[242:243] op_sel_hi:[1,0]
	v_pk_mul_f32 v[80:81], v[80:81], v[242:243] op_sel_hi:[1,0]
	v_lshl_add_u64 v[100:101], v[88:89], 1, v[150:151]
	v_pk_mul_f32 v[88:89], v[96:97], v[242:243] op_sel_hi:[1,0]
	v_pk_mul_f32 v[90:91], v[98:99], v[242:243] op_sel_hi:[1,0]
	v_cvt_pk_bf16_f32 v84, v84, v85
	v_cvt_pk_bf16_f32 v85, v86, v87
	v_cvt_pk_bf16_f32 v86, v80, v81
	v_pk_mul_f32 v[80:81], v[82:83], v[242:243] op_sel_hi:[1,0]
	v_cvt_pk_bf16_f32 v88, v88, v89
	v_cvt_pk_bf16_f32 v89, v90, v91
	v_pk_mul_f32 v[90:91], v[92:93], v[242:243] op_sel_hi:[1,0]
	v_pk_mul_f32 v[92:93], v[94:95], v[242:243] op_sel_hi:[1,0]
	v_cvt_pk_bf16_f32 v87, v80, v81
	v_cvt_pk_bf16_f32 v90, v90, v91
	v_cvt_pk_bf16_f32 v91, v92, v93
	global_store_dwordx4 v[100:101], v[84:87], off offset:256
	v_or_b32_e32 v82, 48, v148
	global_store_dwordx4 v[100:101], v[88:91], off
	v_pk_mul_f32 v[84:85], v[76:77], v[244:245] op_sel_hi:[1,0]
	v_pk_mul_f32 v[86:87], v[78:79], v[244:245] op_sel_hi:[1,0]
	v_mad_i64_i32 v[80:81], s[0:1], s53, v82, 0
	v_cvt_pk_bf16_f32 v84, v84, v85
	v_cvt_pk_bf16_f32 v85, v86, v87
	v_pk_mul_f32 v[86:87], v[72:73], v[244:245] op_sel_hi:[1,0]
	v_pk_mul_f32 v[88:89], v[74:75], v[244:245] op_sel_hi:[1,0]
	v_lshl_add_u64 v[80:81], v[80:81], 1, v[150:151]
	v_cvt_pk_bf16_f32 v86, v86, v87
	v_cvt_pk_bf16_f32 v87, v88, v89
	global_store_dwordx4 v[80:81], v[84:87], off
	v_pk_mul_f32 v[88:89], v[66:67], v[244:245] op_sel_hi:[1,0]
	v_cndmask_b32_e64 v83, 0, 1, s[70:71]
	v_pk_mul_f32 v[84:85], v[68:69], v[244:245] op_sel_hi:[1,0]
	v_pk_mul_f32 v[86:87], v[70:71], v[244:245] op_sel_hi:[1,0]
	v_cvt_pk_bf16_f32 v84, v84, v85
	v_cvt_pk_bf16_f32 v85, v86, v87
	v_pk_mul_f32 v[86:87], v[64:65], v[244:245] op_sel_hi:[1,0]
	v_cmp_ne_u32_e64 s[0:1], 1, v83
	v_cvt_pk_bf16_f32 v86, v86, v87
	v_cvt_pk_bf16_f32 v87, v88, v89
	s_andn2_b64 vcc, exec, s[70:71]
	global_store_dwordx4 v[80:81], v[84:87], off offset:256
	s_cbranch_vccnz .LBB0_201
	v_cmp_lt_i32_e32 vcc, s96, v82
	s_and_saveexec_b64 s[58:59], vcc
	s_xor_b64 s[72:73], exec, s[58:59]
	s_add_i32 s8, s52, 0xffff8030
	s_lshr_b32 s8, s8, 5
	s_mulk_i32 s8, 0x700
	s_lshl_b64 s[58:59], s[8:9], 2
	s_add_u32 s74, s80, s58
	s_addc_u32 s75, s81, s59
	s_or_saveexec_b64 s[72:73], s[72:73]
	v_mov_b64_e32 v[80:81], s[74:75]
	s_mov_b64 s[74:75], s[38:39]
	s_xor_b64 exec, exec, s[72:73]
	s_cbranch_execz .LBB0_198
	s_ashr_i32 s8, s52, 12
	s_mul_i32 s58, s8, 0x700
	s_ashr_i32 s59, s58, 31
	s_lshl_b64 s[58:59], s[58:59], 2
	v_and_b32_e32 v80, 0xfff, v82
	s_add_u32 s58, s16, s58
	v_cmp_eq_u32_e32 vcc, s97, v80
	s_addc_u32 s59, s17, s59
	v_mov_b64_e32 v[80:81], s[58:59]
	s_andn2_b64 s[58:59], s[38:39], exec
	s_and_b64 s[60:61], vcc, exec
	s_or_b64 s[74:75], s[58:59], s[60:61]
.LBB0_198:
	s_or_b64 exec, exec, s[72:73]
	s_and_saveexec_b64 s[72:73], s[74:75]
	s_cbranch_execz .LBB0_200
	v_lshl_add_u64 v[80:81], v[146:147], 2, v[80:81]
	v_pk_mul_f32 v[78:79], v[78:79], v[244:245] op_sel_hi:[1,0]
	v_pk_mul_f32 v[76:77], v[76:77], v[244:245] op_sel_hi:[1,0]
	v_pk_mul_f32 v[74:75], v[74:75], v[244:245] op_sel_hi:[1,0]
	v_pk_mul_f32 v[72:73], v[72:73], v[244:245] op_sel_hi:[1,0]
	v_pk_mul_f32 v[70:71], v[70:71], v[244:245] op_sel_hi:[1,0]
	v_pk_mul_f32 v[68:69], v[68:69], v[244:245] op_sel_hi:[1,0]
	v_pk_mul_f32 v[66:67], v[66:67], v[244:245] op_sel_hi:[1,0]
	v_pk_mul_f32 v[64:65], v[64:65], v[244:245] op_sel_hi:[1,0]
	global_store_dwordx4 v[80:81], v[76:79], off
	global_store_dwordx4 v[80:81], v[72:75], off offset:16
	global_store_dwordx4 v[80:81], v[68:71], off offset:512
	global_store_dwordx4 v[80:81], v[64:67], off offset:528

;     __device__ __forceinline__ void operator()(const f32x4 (&acc)[2][2][4][2], const Unit& u, int wr, int wc, int fr, int fq) const {
;     ...
;             for (int m = 0; m < 4; ++m) {
;                 const int row = row0 + ai * 128 + m * 16; const float s = sv[ai * 4 + m]; bf16_t* rowp = base + (size_t)row * ld + col0;
; #pragma unroll
;                 for (int bj = 0; bj < 2; ++bj) *(u32x4*)(rowp + bj * 128) = pack_acc8(acc[ai][bj][m][0], acc[ai][bj][m][1], s);
;                 if (!hg) {
;                     bool last; float* dst;
;                     if (row < NTOKP) { last = (row & 4095) == 4095; dst = psh + (row >> 12) * RWC; } else { const int rr = row - NTOKP; last = (rr & 31) == 31; dst = ssh + (rr >> 5) * RWC; }
;                     if (last) {
; #pragma unroll
;                         for (int bj = 0; bj < 2; ++bj) { *(f32x4*)(dst + col0 + bj * 128) = acc[ai][bj][m][0] * s; *(f32x4*)(dst + col0 + bj * 128 + 4) = acc[ai][bj][m][1] * s; }
;                     }
;                 }
;             }
.LBB0_201:
	v_pk_mul_f32 v[52:53], v[52:53], v[246:247] op_sel_hi:[1,0]
	v_pk_mul_f32 v[54:55], v[54:55], v[246:247] op_sel_hi:[1,0]
	v_pk_mul_f32 v[48:49], v[48:49], v[246:247] op_sel_hi:[1,0]
	v_add_u32_e32 v64, 0x80, v148
	v_cvt_pk_bf16_f32 v52, v52, v53
	v_cvt_pk_bf16_f32 v53, v54, v55
	v_cvt_pk_bf16_f32 v54, v48, v49
	v_pk_mul_f32 v[48:49], v[50:51], v[246:247] op_sel_hi:[1,0]
	v_mad_i64_i32 v[66:67], s[58:59], s53, v64, 0
	v_cvt_pk_bf16_f32 v55, v48, v49
	v_add_u32_e32 v48, 0x90, v148
	v_lshl_add_u64 v[66:67], v[66:67], 1, v[150:151]
	v_mad_i64_i32 v[48:49], s[58:59], s53, v48, 0
	v_pk_mul_f32 v[60:61], v[60:61], v[246:247] op_sel_hi:[1,0]
	v_pk_mul_f32 v[62:63], v[62:63], v[246:247] op_sel_hi:[1,0]
	v_pk_mul_f32 v[56:57], v[56:57], v[246:247] op_sel_hi:[1,0]
	global_store_dwordx4 v[66:67], v[52:55], off offset:256
	v_pk_mul_f32 v[50:51], v[46:47], v[248:249] op_sel_hi:[1,0]
	v_cvt_pk_bf16_f32 v60, v60, v61
	v_lshl_add_u64 v[52:53], v[48:49], 1, v[150:151]
	v_pk_mul_f32 v[48:49], v[44:45], v[248:249] op_sel_hi:[1,0]
	v_cvt_pk_bf16_f32 v61, v62, v63
	v_cvt_pk_bf16_f32 v62, v56, v57
	v_pk_mul_f32 v[56:57], v[58:59], v[246:247] op_sel_hi:[1,0]
	v_cvt_pk_bf16_f32 v48, v48, v49
	v_cvt_pk_bf16_f32 v49, v50, v51
	v_pk_mul_f32 v[50:51], v[40:41], v[248:249] op_sel_hi:[1,0]
	v_pk_mul_f32 v[54:55], v[42:43], v[248:249] op_sel_hi:[1,0]
	v_cvt_pk_bf16_f32 v63, v56, v57
	v_cvt_pk_bf16_f32 v50, v50, v51
	v_cvt_pk_bf16_f32 v51, v54, v55
	s_movk_i32 s8, 0x7f6f
	global_store_dwordx4 v[66:67], v[60:63], off
	global_store_dwordx4 v[52:53], v[48:51], off
	v_cmp_lt_i32_e32 vcc, s8, v148
	v_pk_mul_f32 v[54:55], v[26:27], v[248:249] op_sel_hi:[1,0]
	v_pk_mul_f32 v[48:49], v[36:37], v[248:249] op_sel_hi:[1,0]
	v_pk_mul_f32 v[50:51], v[38:39], v[248:249] op_sel_hi:[1,0]
	v_cvt_pk_bf16_f32 v48, v48, v49
	v_cvt_pk_bf16_f32 v49, v50, v51
	v_pk_mul_f32 v[50:51], v[24:25], v[248:249] op_sel_hi:[1,0]
	s_and_b64 s[58:59], s[38:39], vcc
	v_cvt_pk_bf16_f32 v50, v50, v51
	v_cvt_pk_bf16_f32 v51, v54, v55
	s_and_b64 s[58:59], s[70:71], s[58:59]
	global_store_dwordx4 v[52:53], v[48:51], off offset:256
	s_and_saveexec_b64 s[70:71], s[58:59]
	s_cbranch_execz .LBB0_203
	s_add_i32 s8, s52, 0xffff8090
	s_lshr_b32 s8, s8, 5
	s_mulk_i32 s8, 0x700
	s_lshl_b64 s[58:59], s[8:9], 2
	s_add_u32 s58, s80, s58
	s_addc_u32 s59, s81, s59
	v_lshl_add_u64 v[48:49], v[146:147], 2, s[58:59]
	v_pk_mul_f32 v[46:47], v[46:47], v[248:249] op_sel_hi:[1,0]
	v_pk_mul_f32 v[44:45], v[44:45], v[248:249] op_sel_hi:[1,0]
	v_pk_mul_f32 v[42:43], v[42:43], v[248:249] op_sel_hi:[1,0]
	v_pk_mul_f32 v[40:41], v[40:41], v[248:249] op_sel_hi:[1,0]
	v_pk_mul_f32 v[38:39], v[38:39], v[248:249] op_sel_hi:[1,0]
	v_pk_mul_f32 v[36:37], v[36:37], v[248:249] op_sel_hi:[1,0]
	v_pk_mul_f32 v[26:27], v[26:27], v[248:249] op_sel_hi:[1,0]
	v_pk_mul_f32 v[24:25], v[24:25], v[248:249] op_sel_hi:[1,0]
	global_store_dwordx4 v[48:49], v[44:47], off
	global_store_dwordx4 v[48:49], v[40:43], off offset:16
	global_store_dwordx4 v[48:49], v[36:39], off offset:512
	global_store_dwordx4 v[48:49], v[24:27], off offset:528
.LBB0_203:
	s_or_b64 exec, exec, s[70:71]
	s_nop 0
	v_add_u32_e32 v24, 0xa0, v148
	v_mad_i64_i32 v[24:25], s[58:59], s53, v24, 0
	v_pk_mul_f32 v[20:21], v[20:21], v[250:251] op_sel_hi:[1,0]
	v_pk_mul_f32 v[22:23], v[22:23], v[250:251] op_sel_hi:[1,0]
	v_pk_mul_f32 v[16:17], v[16:17], v[250:251] op_sel_hi:[1,0]
	v_lshl_add_u64 v[36:37], v[24:25], 1, v[150:151]
	v_pk_mul_f32 v[24:25], v[32:33], v[250:251] op_sel_hi:[1,0]
	v_pk_mul_f32 v[26:27], v[34:35], v[250:251] op_sel_hi:[1,0]
	v_cvt_pk_bf16_f32 v20, v20, v21
	v_cvt_pk_bf16_f32 v21, v22, v23
	v_cvt_pk_bf16_f32 v22, v16, v17
	v_pk_mul_f32 v[16:17], v[18:19], v[250:251] op_sel_hi:[1,0]
	v_cvt_pk_bf16_f32 v24, v24, v25
	v_cvt_pk_bf16_f32 v25, v26, v27
	v_pk_mul_f32 v[26:27], v[28:29], v[250:251] op_sel_hi:[1,0]
	v_pk_mul_f32 v[28:29], v[30:31], v[250:251] op_sel_hi:[1,0]
	v_cvt_pk_bf16_f32 v23, v16, v17
	v_cvt_pk_bf16_f32 v26, v26, v27
	v_cvt_pk_bf16_f32 v27, v28, v29
	global_store_dwordx4 v[36:37], v[20:23], off offset:256
	v_add_u32_e32 v18, 0xb0, v148
	global_store_dwordx4 v[36:37], v[24:27], off
	v_pk_mul_f32 v[20:21], v[12:13], v[252:253] op_sel_hi:[1,0]
	v_pk_mul_f32 v[22:23], v[14:15], v[252:253] op_sel_hi:[1,0]
	v_mad_i64_i32 v[16:17], s[58:59], s53, v18, 0
	v_cvt_pk_bf16_f32 v20, v20, v21
	v_cvt_pk_bf16_f32 v21, v22, v23
	v_pk_mul_f32 v[22:23], v[8:9], v[252:253] op_sel_hi:[1,0]
	v_pk_mul_f32 v[24:25], v[10:11], v[252:253] op_sel_hi:[1,0]
	v_lshl_add_u64 v[16:17], v[16:17], 1, v[150:151]
	v_cvt_pk_bf16_f32 v22, v22, v23
	v_cvt_pk_bf16_f32 v23, v24, v25
	global_store_dwordx4 v[16:17], v[20:23], off
	v_pk_mul_f32 v[24:25], v[2:3], v[252:253] op_sel_hi:[1,0]
	s_and_b64 vcc, exec, s[0:1]
	v_pk_mul_f32 v[20:21], v[4:5], v[252:253] op_sel_hi:[1,0]
	v_pk_mul_f32 v[22:23], v[6:7], v[252:253] op_sel_hi:[1,0]
	v_cvt_pk_bf16_f32 v20, v20, v21
	v_cvt_pk_bf16_f32 v21, v22, v23
	v_pk_mul_f32 v[22:23], v[0:1], v[252:253] op_sel_hi:[1,0]
	s_nop 0
	v_cvt_pk_bf16_f32 v22, v22, v23
	v_cvt_pk_bf16_f32 v23, v24, v25
	global_store_dwordx4 v[16:17], v[20:23], off offset:256
	s_cbranch_vccnz .LBB0_211
	s_movk_i32 s0, 0x7f4f
	v_cmp_lt_i32_e32 vcc, s0, v148
	s_and_saveexec_b64 s[0:1], vcc
	s_xor_b64 s[0:1], exec, s[0:1]
	s_addk_i32 s52, 0x80b0
	s_lshr_b32 s8, s52, 5
	s_mulk_i32 s8, 0x700
	s_lshl_b64 s[52:53], s[8:9], 2
	s_add_u32 s70, s80, s52
	s_addc_u32 s71, s81, s53
	s_or_saveexec_b64 s[0:1], s[0:1]
	v_mov_b64_e32 v[16:17], s[70:71]
	s_mov_b64 s[70:71], s[38:39]
	s_xor_b64 exec, exec, s[0:1]
	v_ashrrev_i32_e32 v16, 12, v64
	v_and_b32_e32 v18, 0xfff, v18
	v_mul_i32_i24_e32 v16, 0x700, v16
	v_cmp_eq_u32_e32 vcc, s97, v18
	v_ashrrev_i32_e32 v17, 31, v16
	s_andn2_b64 s[52:53], s[38:39], exec
	s_and_b64 s[58:59], vcc, exec
	v_lshl_add_u64 v[16:17], v[16:17], 2, s[16:17]
	s_or_b64 s[70:71], s[52:53], s[58:59]
	s_or_b64 exec, exec, s[0:1]
	s_and_saveexec_b64 s[0:1], s[70:71]
	s_cbranch_execz .LBB0_210
	v_lshl_add_u64 v[16:17], v[146:147], 2, v[16:17]
	v_pk_mul_f32 v[14:15], v[14:15], v[252:253] op_sel_hi:[1,0]
	v_pk_mul_f32 v[12:13], v[12:13], v[252:253] op_sel_hi:[1,0]
	v_pk_mul_f32 v[10:11], v[10:11], v[252:253] op_sel_hi:[1,0]
	v_pk_mul_f32 v[8:9], v[8:9], v[252:253] op_sel_hi:[1,0]
	v_pk_mul_f32 v[6:7], v[6:7], v[252:253] op_sel_hi:[1,0]
	v_pk_mul_f32 v[4:5], v[4:5], v[252:253] op_sel_hi:[1,0]
	v_pk_mul_f32 v[2:3], v[2:3], v[252:253] op_sel_hi:[1,0]
	v_pk_mul_f32 v[0:1], v[0:1], v[252:253] op_sel_hi:[1,0]
	global_store_dwordx4 v[16:17], v[12:15], off
	global_store_dwordx4 v[16:17], v[8:11], off offset:16
	global_store_dwordx4 v[16:17], v[4:7], off offset:512
	global_store_dwordx4 v[16:17], v[0:3], off offset:528

; #define LAS __attribute__((address_space(3)))
; __global__ void __launch_bounds__(512, 2) mk_fwd(Params p) {
;     extern __shared__ __attribute__((aligned(16))) unsigned char smem[];
;     LAS unsigned char* lds = (LAS unsigned char*)smem;
	.amdhsa_kernel _Z6mk_fwd6Params
		.amdhsa_group_segment_fixed_size 0
		.amdhsa_private_segment_fixed_size 0
		.amdhsa_kernarg_size 560
		.amdhsa_user_sgpr_count 2
		.amdhsa_user_sgpr_dispatch_ptr 0
		.amdhsa_user_sgpr_queue_ptr 0
		.amdhsa_user_sgpr_kernarg_segment_ptr 1
		.amdhsa_user_sgpr_dispatch_id 0
		.amdhsa_user_sgpr_kernarg_preload_length 0
		.amdhsa_user_sgpr_kernarg_preload_offset 0
		.amdhsa_user_sgpr_private_segment_size 0
		.amdhsa_uses_dynamic_stack 0
		.amdhsa_enable_private_segment 0
		.amdhsa_system_sgpr_workgroup_id_x 1
		.amdhsa_system_sgpr_workgroup_id_y 0
		.amdhsa_system_sgpr_workgroup_id_z 0
		.amdhsa_system_sgpr_workgroup_info 0
		.amdhsa_system_vgpr_workitem_id 2
		.amdhsa_next_free_vgpr 256
		.amdhsa_next_free_sgpr 102
		.amdhsa_accum_offset 256
		.amdhsa_reserve_vcc 1
		.amdhsa_float_round_mode_32 0
		.amdhsa_float_round_mode_16_64 0
		.amdhsa_float_denorm_mode_32 3
		.amdhsa_float_denorm_mode_16_64 3
		.amdhsa_dx10_clamp 1
		.amdhsa_ieee_mode 1
		.amdhsa_fp16_overflow 0
		.amdhsa_tg_split 0
		.amdhsa_exception_fp_ieee_invalid_op 0
		.amdhsa_exception_fp_denorm_src 0
		.amdhsa_exception_fp_ieee_div_zero 0
		.amdhsa_exception_fp_ieee_overflow 0
		.amdhsa_exception_fp_ieee_underflow 0
		.amdhsa_exception_fp_ieee_inexact 0
		.amdhsa_exception_int_div_zero 0
	.end_amdhsa_kernel

; #define LAS __attribute__((address_space(3)))
; __global__ void __launch_bounds__(512, 2) mk_fwd(Params p) {
;     extern __shared__ __attribute__((aligned(16))) unsigned char smem[];
;     LAS unsigned char* lds = (LAS unsigned char*)smem;
amdhsa.kernels:
  - .agpr_count:     0
    .args:
      - .offset:         0
        .size:           304
        .value_kind:     by_value
      - .offset:         304
        .size:           4
        .value_kind:     hidden_block_count_x
      - .offset:         308
        .size:           4
        .value_kind:     hidden_block_count_y
      - .offset:         312
        .size:           4
        .value_kind:     hidden_block_count_z
      - .offset:         316
        .size:           2
        .value_kind:     hidden_group_size_x
      - .offset:         318
        .size:           2
        .value_kind:     hidden_group_size_y
      - .offset:         320
        .size:           2
        .value_kind:     hidden_group_size_z
      - .offset:         322
        .size:           2
        .value_kind:     hidden_remainder_x
      - .offset:         324
        .size:           2
        .value_kind:     hidden_remainder_y
      - .offset:         326
        .size:           2
        .value_kind:     hidden_remainder_z
      - .offset:         344
        .size:           8
        .value_kind:     hidden_global_offset_x
      - .offset:         352
        .size:           8
        .value_kind:     hidden_global_offset_y
      - .offset:         360
        .size:           8
        .value_kind:     hidden_global_offset_z
      - .offset:         368
        .size:           2
        .value_kind:     hidden_grid_dims
      - .offset:         392
        .size:           8
        .value_kind:     hidden_multigrid_sync_arg
      - .offset:         424
        .size:           4
        .value_kind:     hidden_dynamic_lds_size
    .group_segment_fixed_size: 0
    .kernarg_segment_align: 8
    .kernarg_segment_size: 560
    .language:       OpenCL C
    .language_version:
      - 2
      - 0
    .max_flat_workgroup_size: 512
    .name:           _Z6mk_fwd6Params
    .private_segment_fixed_size: 0
    .sgpr_count:     108
    .sgpr_spill_count: 48
    .symbol:         _Z6mk_fwd6Params.kd
    .uniform_work_group_size: 1
    .uses_dynamic_stack: false
    .vgpr_count:     256
    .vgpr_spill_count: 0
    .wavefront_size: 64
